# g3t
# baseline (speedup 1.0000x reference)
; __device__ __forceinline__ unsigned pk2(float lo, float hi) { const f32x2_t v = {lo, hi}; const bf16x2_t b = __builtin_convertvector(v, bf16x2_t); return __builtin_bit_cast(unsigned, b); }
; __device__ __forceinline__ float siluf(float v) { return v * __builtin_amdgcn_rcpf(1.f + __expf(-v)); }
;     __device__ __forceinline__ void operator()(const f32x4 (&acc)[2][2][4][2], const Unit& u, int wr, int wc, int fr, int fq) const {
;         const int row0 = u.pm * BM + wr * 64 + fr, col0 = u.pn * HALF + wc * 32 + 8 * fq;
; #pragma unroll
;         for (int ai = 0; ai < 2; ++ai)
; #pragma unroll
;             for (int m = 0; m < 4; ++m) { bf16* rowp = Hd + (size_t)(row0 + ai * HALF + m * 16) * FFH + col0;
;                 float r[8];
; #pragma unroll
;                 for (int n = 0; n < 2; ++n)
; #pragma unroll
;                     for (int e = 0; e < 4; ++e) { const float g = acc[ai][0][m][n][e], uu = acc[ai][1][m][n][e]; r[n * 4 + e] = siluf(g) * uu; }
;                 u32x4 w; w.x = pk2(r[0], r[1]); w.y = pk2(r[2], r[3]); w.z = pk2(r[4], r[5]); w.w = pk2(r[6], r[7]);
;                 *(u32x4*)rowp = w; }
.LBB0_202:
	v_and_b32_e32 v168, 63, v199
	v_bfe_u32 v169, v199, 4, 2
	v_lshlrev_b32_e32 v169, 2, v169
	v_xor_b32_e32 v169, v168, v169
	v_and_b32_e32 v170, 0x1c0, v199
	v_add_u32_e32 v173, 64, v170
	v_and_b32_e32 v173, 0x200, v173
	v_lshl_add_u32 v170, v170, 4, v173
	v_bfe_u32 v173, v199, 8, 1
	v_mul_u32_u24_e32 v173, 0x1400, v173
	v_add_u32_e32 v170, v170, v173
	v_add_u32_e32 v170, 0x20000, v170
	v_lshl_add_u32 v174, v169, 4, v170
	v_lshrrev_b32_e32 v171, 2, v168
	v_and_b32_e32 v172, 3, v168
	v_lshlrev_b32_e32 v173, 2, v172
	v_xor_b32_e32 v171, v171, v173
	v_lshl_or_b32 v171, v172, 4, v171
	v_lshl_add_u32 v175, v171, 4, v170
	v_mov_b32_e32 v138, v199
	s_lshl_b32 s9, s34, 8
	s_add_i32 s9, s9, s27
	v_bfe_u32 v142, v138, 2, 4
	v_or_b32_e32 v142, s9, v142
	s_lshl_b32 s9, s33, 7
	v_lshlrev_b32_e32 v138, 3, v138
	v_and_or_b32 v138, v138, 24, s9
	v_or_b32_e32 v144, s28, v138
	v_mul_f32_e32 v138, 0xbfb8aa3b, v124
	v_exp_f32_e32 v138, v138
	v_mul_f32_e32 v139, 0xbfb8aa3b, v125
	v_exp_f32_e32 v139, v139
	v_mul_f32_e32 v143, 0xbfb8aa3b, v126
	v_add_f32_e32 v138, 1.0, v138
	v_rcp_f32_e32 v146, v138
	v_add_f32_e32 v138, 1.0, v139
	v_rcp_f32_e32 v147, v138
	v_exp_f32_e32 v143, v143
	v_ashrrev_i32_e32 v145, 31, v144
	v_mov_b64_e32 v[138:139], s[52:53]
	v_pk_mul_f32 v[124:125], v[124:125], v[146:147]
	v_mul_f32_e32 v146, 0xbfb8aa3b, v127
	v_exp_f32_e32 v146, v146
	v_pk_mul_f32 v[116:117], v[124:125], v[116:117]
	v_add_f32_e32 v124, 1.0, v143
	v_mul_f32_e32 v143, 0xbfb8aa3b, v120
	v_add_f32_e32 v125, 1.0, v146
	v_rcp_f32_e32 v124, v124
	v_rcp_f32_e32 v125, v125
	v_exp_f32_e32 v143, v143
	v_mul_f32_e32 v146, 0xbfb8aa3b, v121
	v_exp_f32_e32 v146, v146
	v_pk_mul_f32 v[124:125], v[126:127], v[124:125]
	v_add_f32_e32 v126, 1.0, v143
	v_mul_f32_e32 v143, 0xbfb8aa3b, v122
	v_add_f32_e32 v127, 1.0, v146
	v_exp_f32_e32 v143, v143
	v_mul_f32_e32 v146, 0xbfb8aa3b, v123
	v_exp_f32_e32 v147, v146
	v_rcp_f32_e32 v126, v126
	v_add_f32_e32 v143, 1.0, v143
	v_rcp_f32_e32 v127, v127
	v_rcp_f32_e32 v146, v143
	v_add_f32_e32 v143, 1.0, v147
	v_rcp_f32_e32 v147, v143
	v_pk_mul_f32 v[120:121], v[120:121], v[126:127]
	v_pk_mul_f32 v[118:119], v[124:125], v[118:119]
	v_pk_mul_f32 v[120:121], v[120:121], v[112:113]
	v_pk_mul_f32 v[112:113], v[122:123], v[146:147]
	v_mad_i64_i32 v[148:149], s[16:17], v142, s67, v[138:139]
	v_pk_mul_f32 v[122:123], v[112:113], v[114:115]
	v_cvt_pk_bf16_f32 v115, v118, v119
	v_mul_f32_e32 v118, 0xbfb8aa3b, v108
	v_mul_f32_e32 v119, 0xbfb8aa3b, v109
	v_exp_f32_e32 v118, v118
	v_exp_f32_e32 v119, v119
	v_lshlrev_b64 v[112:113], 1, v[144:145]
	v_lshl_add_u64 v[124:125], v[148:149], 0, v[112:113]
	v_cvt_pk_bf16_f32 v114, v116, v117
	v_cvt_pk_bf16_f32 v116, v120, v121
	v_cvt_pk_bf16_f32 v117, v122, v123
	ds_write_b128 v174, v[114:117]
	ds_read_b128 v[114:117], v175
	s_waitcnt lgkmcnt(0)
	global_store_dwordx4 v[124:125], v[114:117], off
	s_andn2_b64 vcc, exec, s[6:7]
	s_mov_b64 s[6:7], -1
	v_add_f32_e32 v114, 1.0, v118
	v_add_f32_e32 v115, 1.0, v119
	v_rcp_f32_e32 v114, v114
	v_rcp_f32_e32 v115, v115
	v_or_b32_e32 v116, 16, v142
	v_mad_i64_i32 v[116:117], s[16:17], v116, s67, v[138:139]
	v_pk_mul_f32 v[108:109], v[108:109], v[114:115]
	v_mul_f32_e32 v114, 0xbfb8aa3b, v110
	v_mul_f32_e32 v115, 0xbfb8aa3b, v111
	v_exp_f32_e32 v114, v114
	v_exp_f32_e32 v115, v115
	v_pk_mul_f32 v[100:101], v[108:109], v[100:101]
	v_add_f32_e32 v108, 1.0, v114
	v_add_f32_e32 v109, 1.0, v115
	v_mul_f32_e32 v114, 0xbfb8aa3b, v104
	v_mul_f32_e32 v115, 0xbfb8aa3b, v105
	v_rcp_f32_e32 v108, v108
	v_rcp_f32_e32 v109, v109
	v_exp_f32_e32 v114, v114
	v_exp_f32_e32 v115, v115
	v_pk_mul_f32 v[108:109], v[110:111], v[108:109]
	v_add_f32_e32 v110, 1.0, v114
	v_add_f32_e32 v111, 1.0, v115
	v_mul_f32_e32 v114, 0xbfb8aa3b, v106
	v_mul_f32_e32 v115, 0xbfb8aa3b, v107
	v_exp_f32_e32 v114, v114
	v_exp_f32_e32 v115, v115
	v_rcp_f32_e32 v110, v110
	v_rcp_f32_e32 v111, v111
	v_add_f32_e32 v114, 1.0, v114
	v_add_f32_e32 v115, 1.0, v115
	v_rcp_f32_e32 v114, v114
	v_rcp_f32_e32 v115, v115
	v_pk_mul_f32 v[104:105], v[104:105], v[110:111]
	v_pk_mul_f32 v[102:103], v[108:109], v[102:103]
	v_pk_mul_f32 v[104:105], v[104:105], v[96:97]
	v_pk_mul_f32 v[96:97], v[106:107], v[114:115]
	v_lshl_add_u64 v[108:109], v[116:117], 0, v[112:113]
	v_pk_mul_f32 v[106:107], v[96:97], v[98:99]
	v_cvt_pk_bf16_f32 v96, v100, v101
	v_mul_f32_e32 v100, 0xbfb8aa3b, v92
	v_mul_f32_e32 v101, 0xbfb8aa3b, v93
	v_exp_f32_e32 v100, v100
	v_exp_f32_e32 v101, v101
	v_cvt_pk_bf16_f32 v97, v102, v103
	v_cvt_pk_bf16_f32 v98, v104, v105
	v_cvt_pk_bf16_f32 v99, v106, v107
	ds_write_b128 v174, v[96:99]
	ds_read_b128 v[96:99], v175
	s_waitcnt lgkmcnt(0)
	global_store_dwordx4 v[108:109], v[96:99], off
	s_nop 1
	v_add_f32_e32 v96, 1.0, v100
	v_add_f32_e32 v97, 1.0, v101
	v_rcp_f32_e32 v96, v96
	v_rcp_f32_e32 v97, v97
	v_or_b32_e32 v98, 32, v142
	v_mad_i64_i32 v[98:99], s[16:17], v98, s67, v[138:139]
	v_pk_mul_f32 v[92:93], v[92:93], v[96:97]
	v_mul_f32_e32 v96, 0xbfb8aa3b, v94
	v_mul_f32_e32 v97, 0xbfb8aa3b, v95
	v_exp_f32_e32 v96, v96
	v_exp_f32_e32 v97, v97
	v_pk_mul_f32 v[84:85], v[92:93], v[84:85]
	v_add_f32_e32 v92, 1.0, v96
	v_add_f32_e32 v93, 1.0, v97
	v_mul_f32_e32 v96, 0xbfb8aa3b, v88
	v_mul_f32_e32 v97, 0xbfb8aa3b, v89
	v_rcp_f32_e32 v92, v92
	v_rcp_f32_e32 v93, v93
	v_exp_f32_e32 v96, v96
	v_exp_f32_e32 v97, v97
	v_pk_mul_f32 v[92:93], v[94:95], v[92:93]
	v_add_f32_e32 v94, 1.0, v96
	v_add_f32_e32 v95, 1.0, v97
	v_mul_f32_e32 v96, 0xbfb8aa3b, v90
	v_mul_f32_e32 v97, 0xbfb8aa3b, v91
	v_exp_f32_e32 v96, v96
	v_exp_f32_e32 v97, v97
	v_rcp_f32_e32 v94, v94
	v_rcp_f32_e32 v95, v95
	v_add_f32_e32 v96, 1.0, v96
	v_add_f32_e32 v97, 1.0, v97
	v_rcp_f32_e32 v96, v96
	v_rcp_f32_e32 v97, v97
	v_pk_mul_f32 v[88:89], v[88:89], v[94:95]
	v_pk_mul_f32 v[86:87], v[92:93], v[86:87]
	v_pk_mul_f32 v[88:89], v[88:89], v[80:81]
	v_pk_mul_f32 v[80:81], v[90:91], v[96:97]
	v_lshl_add_u64 v[92:93], v[98:99], 0, v[112:113]
	v_pk_mul_f32 v[90:91], v[80:81], v[82:83]
	v_cvt_pk_bf16_f32 v80, v84, v85
	v_mul_f32_e32 v84, 0xbfb8aa3b, v76
	v_mul_f32_e32 v85, 0xbfb8aa3b, v77
	v_exp_f32_e32 v84, v84
	v_exp_f32_e32 v85, v85
	v_cvt_pk_bf16_f32 v81, v86, v87
	v_cvt_pk_bf16_f32 v82, v88, v89
	v_cvt_pk_bf16_f32 v83, v90, v91
	ds_write_b128 v174, v[80:83]
	ds_read_b128 v[80:83], v175
	s_waitcnt lgkmcnt(0)
; __device__ __forceinline__ unsigned pk2(float lo, float hi) { const f32x2_t v = {lo, hi}; const bf16x2_t b = __builtin_convertvector(v, bf16x2_t); return __builtin_bit_cast(unsigned, b); }
; __device__ __forceinline__ float siluf(float v) { return v * __builtin_amdgcn_rcpf(1.f + __expf(-v)); }
;     __device__ __forceinline__ void operator()(const f32x4 (&acc)[2][2][4][2], const Unit& u, int wr, int wc, int fr, int fq) const {
;     ...
;             for (int m = 0; m < 4; ++m) { bf16* rowp = Hd + (size_t)(row0 + ai * HALF + m * 16) * FFH + col0;
;                 float r[8];
; #pragma unroll
;                 for (int n = 0; n < 2; ++n)
; #pragma unroll
;                     for (int e = 0; e < 4; ++e) { const float g = acc[ai][0][m][n][e], uu = acc[ai][1][m][n][e]; r[n * 4 + e] = siluf(g) * uu; }
;                 u32x4 w; w.x = pk2(r[0], r[1]); w.y = pk2(r[2], r[3]); w.z = pk2(r[4], r[5]); w.w = pk2(r[6], r[7]);
;                 *(u32x4*)rowp = w; }
	global_store_dwordx4 v[92:93], v[80:83], off
	s_nop 1
	v_add_f32_e32 v80, 1.0, v84
	v_add_f32_e32 v81, 1.0, v85
	v_rcp_f32_e32 v80, v80
	v_rcp_f32_e32 v81, v81
	v_or_b32_e32 v82, 48, v142
	v_mad_i64_i32 v[82:83], s[16:17], v82, s67, v[138:139]
	v_pk_mul_f32 v[76:77], v[76:77], v[80:81]
	v_mul_f32_e32 v80, 0xbfb8aa3b, v78
	v_mul_f32_e32 v81, 0xbfb8aa3b, v79
	v_exp_f32_e32 v80, v80
	v_exp_f32_e32 v81, v81
	v_pk_mul_f32 v[68:69], v[76:77], v[68:69]
	v_add_f32_e32 v76, 1.0, v80
	v_add_f32_e32 v77, 1.0, v81
	v_mul_f32_e32 v80, 0xbfb8aa3b, v72
	v_mul_f32_e32 v81, 0xbfb8aa3b, v73
	v_rcp_f32_e32 v76, v76
	v_rcp_f32_e32 v77, v77
	v_exp_f32_e32 v80, v80
	v_exp_f32_e32 v81, v81
	v_pk_mul_f32 v[76:77], v[78:79], v[76:77]
	v_add_f32_e32 v78, 1.0, v80
	v_add_f32_e32 v79, 1.0, v81
	v_mul_f32_e32 v80, 0xbfb8aa3b, v74
	v_mul_f32_e32 v81, 0xbfb8aa3b, v75
	v_exp_f32_e32 v80, v80
	v_exp_f32_e32 v81, v81
	v_rcp_f32_e32 v78, v78
	v_rcp_f32_e32 v79, v79
	v_add_f32_e32 v80, 1.0, v80
	v_add_f32_e32 v81, 1.0, v81
	v_rcp_f32_e32 v80, v80
	v_rcp_f32_e32 v81, v81
	v_pk_mul_f32 v[72:73], v[72:73], v[78:79]
	v_pk_mul_f32 v[70:71], v[76:77], v[70:71]
	v_pk_mul_f32 v[72:73], v[72:73], v[64:65]
	v_pk_mul_f32 v[64:65], v[74:75], v[80:81]
	v_lshl_add_u64 v[76:77], v[82:83], 0, v[112:113]
	v_pk_mul_f32 v[74:75], v[64:65], v[66:67]
	v_cvt_pk_bf16_f32 v64, v68, v69
	v_mul_f32_e32 v68, 0xbfb8aa3b, v60
	v_mul_f32_e32 v69, 0xbfb8aa3b, v61
	v_exp_f32_e32 v68, v68
	v_exp_f32_e32 v69, v69
	v_cvt_pk_bf16_f32 v65, v70, v71
	v_cvt_pk_bf16_f32 v66, v72, v73
	v_cvt_pk_bf16_f32 v67, v74, v75
	ds_write_b128 v174, v[64:67]
	ds_read_b128 v[64:67], v175
	s_waitcnt lgkmcnt(0)
	global_store_dwordx4 v[76:77], v[64:67], off
	s_nop 1
	v_add_f32_e32 v64, 1.0, v68
	v_add_f32_e32 v65, 1.0, v69
	v_rcp_f32_e32 v64, v64
	v_rcp_f32_e32 v65, v65
	v_add_u32_e32 v66, 0x80, v142
	v_mad_i64_i32 v[66:67], s[16:17], v66, s67, v[138:139]
	v_pk_mul_f32 v[60:61], v[60:61], v[64:65]
	v_mul_f32_e32 v64, 0xbfb8aa3b, v62
	v_mul_f32_e32 v65, 0xbfb8aa3b, v63
	v_exp_f32_e32 v64, v64
	v_exp_f32_e32 v65, v65
	v_pk_mul_f32 v[52:53], v[60:61], v[52:53]
	v_add_f32_e32 v60, 1.0, v64
	v_add_f32_e32 v61, 1.0, v65
	v_mul_f32_e32 v64, 0xbfb8aa3b, v56
	v_mul_f32_e32 v65, 0xbfb8aa3b, v57
	v_rcp_f32_e32 v60, v60
	v_rcp_f32_e32 v61, v61
	v_exp_f32_e32 v64, v64
	v_exp_f32_e32 v65, v65
	v_pk_mul_f32 v[60:61], v[62:63], v[60:61]
	v_add_f32_e32 v62, 1.0, v64
	v_add_f32_e32 v63, 1.0, v65
	v_mul_f32_e32 v64, 0xbfb8aa3b, v58
	v_mul_f32_e32 v65, 0xbfb8aa3b, v59
	v_exp_f32_e32 v64, v64
	v_exp_f32_e32 v65, v65
	v_rcp_f32_e32 v62, v62
	v_rcp_f32_e32 v63, v63
	v_add_f32_e32 v64, 1.0, v64
	v_add_f32_e32 v65, 1.0, v65
	v_rcp_f32_e32 v64, v64
	v_rcp_f32_e32 v65, v65
	v_pk_mul_f32 v[56:57], v[56:57], v[62:63]
	v_pk_mul_f32 v[54:55], v[60:61], v[54:55]
	v_pk_mul_f32 v[56:57], v[56:57], v[48:49]
	v_pk_mul_f32 v[48:49], v[58:59], v[64:65]
	v_lshl_add_u64 v[60:61], v[66:67], 0, v[112:113]
	v_pk_mul_f32 v[58:59], v[48:49], v[50:51]
	v_cvt_pk_bf16_f32 v48, v52, v53
	v_mul_f32_e32 v52, 0xbfb8aa3b, v44
	v_mul_f32_e32 v53, 0xbfb8aa3b, v45
	v_exp_f32_e32 v52, v52
	v_exp_f32_e32 v53, v53
	v_cvt_pk_bf16_f32 v49, v54, v55
	v_cvt_pk_bf16_f32 v50, v56, v57
	v_cvt_pk_bf16_f32 v51, v58, v59
	ds_write_b128 v174, v[48:51]
	ds_read_b128 v[48:51], v175
	s_waitcnt lgkmcnt(0)
	global_store_dwordx4 v[60:61], v[48:51], off
	s_nop 1
	v_add_f32_e32 v48, 1.0, v52
	v_add_f32_e32 v49, 1.0, v53
	v_rcp_f32_e32 v48, v48
	v_rcp_f32_e32 v49, v49
	v_add_u32_e32 v50, 0x90, v142
	v_mad_i64_i32 v[50:51], s[16:17], v50, s67, v[138:139]
	v_pk_mul_f32 v[44:45], v[44:45], v[48:49]
	v_mul_f32_e32 v48, 0xbfb8aa3b, v46
	v_mul_f32_e32 v49, 0xbfb8aa3b, v47
	v_exp_f32_e32 v48, v48
	v_exp_f32_e32 v49, v49
	v_pk_mul_f32 v[36:37], v[44:45], v[36:37]
	v_add_f32_e32 v44, 1.0, v48
	v_add_f32_e32 v45, 1.0, v49
	v_mul_f32_e32 v48, 0xbfb8aa3b, v40
	v_mul_f32_e32 v49, 0xbfb8aa3b, v41
	v_rcp_f32_e32 v44, v44
	v_rcp_f32_e32 v45, v45
	v_exp_f32_e32 v48, v48
	v_exp_f32_e32 v49, v49
	v_pk_mul_f32 v[44:45], v[46:47], v[44:45]
	v_add_f32_e32 v46, 1.0, v48
	v_add_f32_e32 v47, 1.0, v49
	v_mul_f32_e32 v48, 0xbfb8aa3b, v42
	v_mul_f32_e32 v49, 0xbfb8aa3b, v43
	v_exp_f32_e32 v48, v48
	v_exp_f32_e32 v49, v49
	v_rcp_f32_e32 v46, v46
	v_rcp_f32_e32 v47, v47
	v_add_f32_e32 v48, 1.0, v48
	v_add_f32_e32 v49, 1.0, v49
	v_rcp_f32_e32 v48, v48
	v_rcp_f32_e32 v49, v49
	v_pk_mul_f32 v[40:41], v[40:41], v[46:47]
	v_pk_mul_f32 v[38:39], v[44:45], v[38:39]
	v_pk_mul_f32 v[40:41], v[40:41], v[32:33]
	v_pk_mul_f32 v[32:33], v[42:43], v[48:49]
	v_lshl_add_u64 v[44:45], v[50:51], 0, v[112:113]
	v_pk_mul_f32 v[42:43], v[32:33], v[34:35]
	v_cvt_pk_bf16_f32 v32, v36, v37
	v_mul_f32_e32 v36, 0xbfb8aa3b, v28
	v_mul_f32_e32 v37, 0xbfb8aa3b, v29
	v_exp_f32_e32 v36, v36
	v_exp_f32_e32 v37, v37
	v_cvt_pk_bf16_f32 v33, v38, v39
	v_cvt_pk_bf16_f32 v34, v40, v41
	v_cvt_pk_bf16_f32 v35, v42, v43
	ds_write_b128 v174, v[32:35]
	ds_read_b128 v[32:35], v175
	s_waitcnt lgkmcnt(0)
; __device__ __forceinline__ unsigned pk2(float lo, float hi) { const f32x2_t v = {lo, hi}; const bf16x2_t b = __builtin_convertvector(v, bf16x2_t); return __builtin_bit_cast(unsigned, b); }
; __device__ __forceinline__ float siluf(float v) { return v * __builtin_amdgcn_rcpf(1.f + __expf(-v)); }
; #define PG8_BAR __builtin_amdgcn_s_barrier()
;     __device__ __forceinline__ void operator()(const f32x4 (&acc)[2][2][4][2], const Unit& u, int wr, int wc, int fr, int fq) const {
;     ...
;             for (int m = 0; m < 4; ++m) { bf16* rowp = Hd + (size_t)(row0 + ai * HALF + m * 16) * FFH + col0;
;                 float r[8];
; #pragma unroll
;                 for (int n = 0; n < 2; ++n)
; #pragma unroll
;                     for (int e = 0; e < 4; ++e) { const float g = acc[ai][0][m][n][e], uu = acc[ai][1][m][n][e]; r[n * 4 + e] = siluf(g) * uu; }
;                 u32x4 w; w.x = pk2(r[0], r[1]); w.y = pk2(r[2], r[3]); w.z = pk2(r[4], r[5]); w.w = pk2(r[6], r[7]);
;                 *(u32x4*)rowp = w; }
; template <class Epi, int N_, int K_, int LDA_>
; __device__ __forceinline__ void gemm_phase(LAS unsigned char* lds, const Gemm g, const Epi& E) {
;     ...
;         if (!has_next) break;
; #pragma unroll
;         for (int a = 0; a < 2; ++a)
; #pragma unroll
;             for (int b = 0; b < 2; ++b)
; #pragma unroll
;                 for (int m = 0; m < 4; ++m)
; #pragma unroll
;                     for (int n = 0; n < 2; ++n) acc[a][b][m][n] = (f32x4){0.f, 0.f, 0.f, 0.f};
;         cur = nxt; cA = nA; cB = nB; ++ui;
;         if (wr == 1) PG8_BAR;
	global_store_dwordx4 v[44:45], v[32:35], off
	s_nop 1
	v_add_f32_e32 v32, 1.0, v36
	v_add_f32_e32 v33, 1.0, v37
	v_rcp_f32_e32 v32, v32
	v_rcp_f32_e32 v33, v33
	v_add_u32_e32 v34, 0xa0, v142
	v_mad_i64_i32 v[34:35], s[16:17], v34, s67, v[138:139]
	v_pk_mul_f32 v[28:29], v[28:29], v[32:33]
	v_mul_f32_e32 v32, 0xbfb8aa3b, v30
	v_mul_f32_e32 v33, 0xbfb8aa3b, v31
	v_exp_f32_e32 v32, v32
	v_exp_f32_e32 v33, v33
	v_pk_mul_f32 v[20:21], v[28:29], v[20:21]
	v_add_f32_e32 v28, 1.0, v32
	v_add_f32_e32 v29, 1.0, v33
	v_mul_f32_e32 v32, 0xbfb8aa3b, v24
	v_mul_f32_e32 v33, 0xbfb8aa3b, v25
	v_rcp_f32_e32 v28, v28
	v_rcp_f32_e32 v29, v29
	v_exp_f32_e32 v32, v32
	v_exp_f32_e32 v33, v33
	v_pk_mul_f32 v[28:29], v[30:31], v[28:29]
	v_add_f32_e32 v30, 1.0, v32
	v_add_f32_e32 v31, 1.0, v33
	v_mul_f32_e32 v32, 0xbfb8aa3b, v26
	v_mul_f32_e32 v33, 0xbfb8aa3b, v27
	v_exp_f32_e32 v32, v32
	v_exp_f32_e32 v33, v33
	v_rcp_f32_e32 v30, v30
	v_rcp_f32_e32 v31, v31
	v_add_f32_e32 v32, 1.0, v32
	v_add_f32_e32 v33, 1.0, v33
	v_rcp_f32_e32 v32, v32
	v_rcp_f32_e32 v33, v33
	v_pk_mul_f32 v[24:25], v[24:25], v[30:31]
	v_pk_mul_f32 v[22:23], v[28:29], v[22:23]
	v_pk_mul_f32 v[24:25], v[24:25], v[16:17]
	v_pk_mul_f32 v[16:17], v[26:27], v[32:33]
	v_lshl_add_u64 v[28:29], v[34:35], 0, v[112:113]
	v_pk_mul_f32 v[26:27], v[16:17], v[18:19]
	v_cvt_pk_bf16_f32 v16, v20, v21
	v_mul_f32_e32 v20, 0xbfb8aa3b, v12
	v_mul_f32_e32 v21, 0xbfb8aa3b, v13
	v_exp_f32_e32 v20, v20
	v_exp_f32_e32 v21, v21
	v_cvt_pk_bf16_f32 v17, v22, v23
	v_cvt_pk_bf16_f32 v18, v24, v25
	v_cvt_pk_bf16_f32 v19, v26, v27
	ds_write_b128 v174, v[16:19]
	ds_read_b128 v[16:19], v175
	s_waitcnt lgkmcnt(0)
	global_store_dwordx4 v[28:29], v[16:19], off
	s_nop 1
	v_add_f32_e32 v16, 1.0, v20
	v_add_f32_e32 v17, 1.0, v21
	v_rcp_f32_e32 v16, v16
	v_rcp_f32_e32 v17, v17
	v_add_u32_e32 v18, 0xb0, v142
	v_mad_i64_i32 v[18:19], s[16:17], v18, s67, v[138:139]
	v_pk_mul_f32 v[12:13], v[12:13], v[16:17]
	v_mul_f32_e32 v16, 0xbfb8aa3b, v14
	v_mul_f32_e32 v17, 0xbfb8aa3b, v15
	v_exp_f32_e32 v16, v16
	v_exp_f32_e32 v17, v17
	v_pk_mul_f32 v[4:5], v[12:13], v[4:5]
	v_add_f32_e32 v12, 1.0, v16
	v_add_f32_e32 v13, 1.0, v17
	v_mul_f32_e32 v16, 0xbfb8aa3b, v8
	v_mul_f32_e32 v17, 0xbfb8aa3b, v9
	v_rcp_f32_e32 v12, v12
	v_rcp_f32_e32 v13, v13
	v_exp_f32_e32 v16, v16
	v_exp_f32_e32 v17, v17
	v_pk_mul_f32 v[12:13], v[14:15], v[12:13]
	v_add_f32_e32 v14, 1.0, v16
	v_add_f32_e32 v15, 1.0, v17
	v_mul_f32_e32 v16, 0xbfb8aa3b, v10
	v_mul_f32_e32 v17, 0xbfb8aa3b, v11
	v_exp_f32_e32 v16, v16
	v_exp_f32_e32 v17, v17
	v_rcp_f32_e32 v14, v14
	v_rcp_f32_e32 v15, v15
	v_add_f32_e32 v16, 1.0, v16
	v_add_f32_e32 v17, 1.0, v17
	v_rcp_f32_e32 v16, v16
	v_rcp_f32_e32 v17, v17
	v_pk_mul_f32 v[8:9], v[8:9], v[14:15]
	v_pk_mul_f32 v[6:7], v[12:13], v[6:7]
	v_pk_mul_f32 v[8:9], v[8:9], v[0:1]
	v_pk_mul_f32 v[0:1], v[10:11], v[16:17]
	v_lshl_add_u64 v[12:13], v[18:19], 0, v[112:113]
	v_pk_mul_f32 v[10:11], v[0:1], v[2:3]
	v_cvt_pk_bf16_f32 v0, v4, v5
	v_cvt_pk_bf16_f32 v1, v6, v7
	v_cvt_pk_bf16_f32 v2, v8, v9
	v_cvt_pk_bf16_f32 v3, v10, v11
	ds_write_b128 v174, v[0:3]
	ds_read_b128 v[0:3], v175
	s_waitcnt lgkmcnt(0)
	global_store_dwordx4 v[12:13], v[0:3], off
	s_cbranch_vccnz .LBB0_195
	s_andn2_b64 vcc, exec, s[0:1]
	s_cbranch_vccnz .LBB0_194
	s_barrier
	s_branch .LBB0_194
